# SwiGLU GEMM: per-workgroup cyclic K rotation (r = (pm_local+pn_local) mod 8) so tile-sharing workgroups request different K slices at a time (L2 hits instead of concurrent misses)
# baseline (speedup 1.0000x reference)
.LBB0_139:
	s_and_b64 vcc, exec, s[8:9]
	s_cbranch_vccz .LBB0_152
	v_readlane_b32 s99, v255, 18
	s_lshr_b32 s99, s99, 3
	s_and_b32 s101, s99, 7
	s_lshr_b32 s99, s99, 3
	s_add_i32 s101, s101, s99
	s_and_b32 s101, s101, 7
	s_sub_i32 s99, 7, s101
	s_lshl_b32 s99, s99, 1
	s_add_i32 s99, s99, -2
	s_lshl_b32 s101, s101, 8
	s_mov_b32 s35, s46
	s_mov_b32 s37, s87
	s_waitcnt vmcnt(0)
	v_mov_b32_e32 v8, v228
	s_cmpk_gt_i32 s37, 0xaff
	v_readfirstlane_b32 s48, v8
	s_cbranch_scc1 .LBB0_152
	v_lshlrev_b32_e32 v0, 4, v8
	v_add_u32_e32 v1, 0x2000, v0
	v_ashrrev_i32_e32 v2, 31, v1
	v_lshrrev_b32_e32 v2, 22, v2
	v_add_u32_e32 v2, v1, v2
	v_ashrrev_i32_e32 v9, 10, v2
	v_mul_i32_i24_e32 v2, 0x400, v9
	v_sub_u32_e32 v1, v1, v2
	v_lshrrev_b32_e32 v2, 4, v1
	v_bitop3_b32 v1, v2, v1, 32 bitop3:0x6c
	v_ashrrev_i32_e32 v2, 31, v1
	v_lshrrev_b32_e32 v2, 26, v2
	v_add_u32_e32 v2, v1, v2
	v_lshlrev_b32_e32 v3, 3, v9
	v_ashrrev_i32_e32 v10, 6, v2
	v_and_b32_e32 v3, -16, v3
	v_add_u32_e32 v3, v10, v3
	v_and_b32_e32 v4, 3, v10
	s_mov_b32 s8, 0x1fffe0
	v_lshrrev_b32_e32 v5, 2, v3
	v_lshlrev_b32_e32 v6, 1, v3
	v_and_b32_e32 v2, 0xc0, v2
	v_and_or_b32 v4, v3, s8, v4
	v_and_b32_e32 v5, 4, v5
	v_and_b32_e32 v6, 24, v6
	v_sub_u32_e32 v1, v1, v2
	v_or3_b32 v4, v4, v5, v6
	v_lshlrev_b32_e32 v5, 5, v9
	v_ashrrev_i16_sdwa v1, v230, sext(v1) dst_sel:DWORD dst_unused:UNUSED_PAD src0_sel:DWORD src1_sel:BYTE_0
	v_and_b32_e32 v5, 32, v5
	v_bfe_i32 v11, v1, 0, 16
	v_add_lshl_u32 v1, v5, v11, 1
	v_lshl_add_u32 v130, v4, 11, v1
	v_lshl_add_u32 v132, v3, 11, v1
	v_bfe_i32 v1, v8, 27, 1
	v_lshrrev_b32_e32 v1, 22, v1
	v_add_u32_e32 v1, v0, v1
	v_and_b32_e32 v1, 0xfffffc00, v1
	v_sub_u32_e32 v0, v0, v1
	v_lshrrev_b32_e32 v1, 4, v0
	v_bitop3_b32 v1, v1, v0, 32 bitop3:0x6c
	v_ashrrev_i32_e32 v0, 31, v0
	v_lshrrev_b32_e32 v0, 26, v0
	v_add_u32_e32 v0, v1, v0
	v_ashrrev_i32_e32 v12, 6, v0
	v_ashrrev_i32_e32 v0, 31, v8
	v_lshrrev_b32_e32 v0, 26, v0
	v_add_u32_e32 v0, v8, v0
	s_cmp_eq_u32 s13, 1
	v_ashrrev_i32_e32 v13, 6, v0
	s_cselect_b32 s2, 0, 0x2800000
	v_lshlrev_b32_e32 v0, 3, v13
	s_add_u32 s49, s44, s2
	v_and_b32_e32 v0, -16, v0
	s_addc_u32 s50, s45, 0
	v_add_u32_e32 v0, v12, v0
	v_and_b32_e32 v2, 3, v12
	s_ashr_i32 s52, s37, 31
	v_and_or_b32 v2, v0, s8, v2
	s_lshr_b32 s8, s52, 29
	s_add_i32 s8, s37, s8
	s_ashr_i32 s2, s48, 6
	s_ashr_i32 s12, s8, 3
	s_and_b32 s8, s8, -8
	s_ashr_i32 s9, s48, 8
	s_lshl_b32 s51, s2, 10
	s_sub_i32 s8, s37, s8
	s_cmp_lt_i32 s8, 0
	s_movk_i32 s14, 0x161
	s_cselect_b32 s14, s14, 0x160
	s_mul_i32 s8, s14, s8
	s_add_i32 s8, s8, s12
	s_mul_hi_i32 s12, s8, 0x2e8ba2e9
	s_lshr_b32 s14, s12, 31
	s_ashr_i32 s12, s12, 5
	s_add_i32 s12, s12, s14
	s_lshl_b32 s14, s12, 3
	s_mulk_i32 s12, 0xb0
	s_sub_i32 s12, s8, s12
	s_bfe_u32 s8, s12, 0x3001c
	s_add_i32 s15, s12, s8
	s_sext_i32_i16 s8, s15
	s_and_b32 s15, s15, 0xfff8
	v_lshrrev_b32_e32 v3, 2, v0
	v_lshlrev_b32_e32 v4, 1, v0
	s_sub_i32 s12, s12, s15
	v_and_b32_e32 v3, 4, v3
	v_and_b32_e32 v4, 24, v4
	s_sext_i32_i16 s12, s12
	v_or3_b32 v2, v2, v3, v4
	v_mul_i32_i24_e32 v4, 64, v12
	s_lshr_b32 s8, s8, 3
	s_add_i32 s14, s14, s12
	v_sub_u32_e32 v1, v1, v4
	s_ashr_i32 s15, s14, 31
	s_bfe_i64 s[16:17], s[8:9], 0x100000
	v_lshlrev_b32_e32 v3, 5, v13
	v_ashrrev_i16_sdwa v1, v230, sext(v1) dst_sel:DWORD dst_unused:UNUSED_PAD src0_sel:DWORD src1_sel:BYTE_0
	s_lshl_b64 s[18:19], s[14:15], 19
	s_lshl_b64 s[16:17], s[16:17], 19
	v_and_b32_e32 v3, 32, v3
	v_bfe_i32 v14, v1, 0, 16
	s_add_u32 s16, s49, s16
	v_add_lshl_u32 v1, v3, v14, 1
	s_addc_u32 s17, s50, s17
	s_add_u32 s16, s16, s101
	s_addc_u32 s17, s17, 0
	s_add_i32 s15, s51, 0
	v_lshl_add_u32 v16, v2, 11, v1
	s_add_i32 m0, s15, 0x10000
	v_lshl_add_u32 v134, v0, 11, v1
	global_load_lds_dwordx4 v16, s[16:17]
	s_add_i32 m0, s15, 0x12000
	s_add_u32 s18, s30, s18
	global_load_lds_dwordx4 v130, s[16:17]
	s_addc_u32 s19, s31, s19
	s_add_u32 s18, s18, s101
	s_addc_u32 s19, s19, 0
	s_mov_b32 m0, s15
	s_add_i32 s54, s15, 0x2000
	global_load_lds_dwordx4 v134, s[18:19]
	s_mov_b32 m0, s54
	s_add_u32 s22, s16, 0x40000
	global_load_lds_dwordx4 v132, s[18:19]
	s_addc_u32 s23, s17, 0
	s_add_i32 m0, s15, 0x14000
	v_mov_b32_e32 v131, v17
	global_load_lds_dwordx4 v16, s[22:23]
	s_add_i32 m0, s15, 0x16000
	v_mov_b32_e32 v135, v17
	global_load_lds_dwordx4 v130, s[22:23]
	s_add_u32 s22, s18, 0x40000
	s_addc_u32 s23, s19, 0
	s_add_i32 s55, s15, 0x4000
	s_mov_b32 m0, s55
	s_add_i32 s56, s15, 0x6000
	global_load_lds_dwordx4 v134, s[22:23]
	s_mov_b32 m0, s56
	v_mov_b32_e32 v133, v17
	global_load_lds_dwordx4 v132, s[22:23]
	v_lshl_add_u64 v[6:7], s[16:17], 0, v[16:17]
	v_lshl_add_u64 v[4:5], s[16:17], 0, v[130:131]
	v_lshl_add_u64 v[2:3], s[18:19], 0, v[134:135]
	s_cmp_lg_u32 s9, 1
	v_lshl_add_u64 v[0:1], s[18:19], 0, v[132:133]
	s_cbranch_scc1 .LBB0_143
	s_barrier

.LBB0_146:
	s_ashr_i32 s29, s28, 31
	v_cmp_lt_i64_e32 vcc, s[22:23], v[198:199]
	s_lshl_b64 s[22:23], s[28:29], 19
	s_add_u32 s40, s30, s22
	s_addc_u32 s41, s31, s23
	s_add_u32 s40, s40, s101
	s_addc_u32 s41, s41, 0
	s_and_b64 s[22:23], vcc, exec
	s_cselect_b32 s12, s41, s19
	s_cselect_b32 s29, s40, s18
	s_ashr_i32 s9, s8, 31
	s_lshl_b64 s[22:23], s[8:9], 19
	s_add_u32 s42, s49, s22
	s_addc_u32 s43, s50, s23
	s_add_u32 s42, s42, s101
	s_addc_u32 s43, s43, 0
	s_and_b64 s[22:23], vcc, exec
	s_cselect_b32 s9, s43, s17
	s_cselect_b32 s34, s42, s16
	s_add_u32 s61, s16, 0x100
	s_addc_u32 s79, s17, 0
	s_add_u32 s16, s18, 0x40080
	v_mov_b32_e32 v0, 0
	s_addc_u32 s17, s19, 0
	s_mov_b32 s82, -2
	v_mov_b32_e32 v1, v0
	v_mov_b64_e32 v[2:3], 0
	v_mov_b64_e32 v[8:9], 0
	v_mov_b64_e32 v[10:11], 0
	v_mov_b64_e32 v[18:19], 0
	v_mov_b64_e32 v[20:21], 0
	v_mov_b64_e32 v[26:27], 0
	v_mov_b64_e32 v[28:29], 0
	s_waitcnt lgkmcnt(0)
	v_mov_b64_e32 v[34:35], 0
	v_mov_b64_e32 v[36:37], 0
	v_mov_b64_e32 v[42:43], 0
	v_mov_b64_e32 v[44:45], 0
	v_mov_b64_e32 v[50:51], 0
	v_mov_b64_e32 v[52:53], 0
	v_mov_b64_e32 v[58:59], 0
	v_mov_b64_e32 v[60:61], 0
	v_mov_b64_e32 v[4:5], 0
	v_mov_b64_e32 v[6:7], 0
	v_mov_b64_e32 v[12:13], 0
	v_mov_b64_e32 v[14:15], 0
	v_mov_b64_e32 v[22:23], 0
	v_mov_b64_e32 v[24:25], 0
	v_mov_b64_e32 v[30:31], 0
	v_mov_b64_e32 v[32:33], 0
	v_mov_b64_e32 v[38:39], 0
	v_mov_b64_e32 v[40:41], 0
	v_mov_b64_e32 v[46:47], 0
	v_mov_b64_e32 v[48:49], 0
	v_mov_b64_e32 v[54:55], 0
	v_mov_b64_e32 v[56:57], 0
	v_mov_b64_e32 v[62:63], 0
	v_mov_b64_e32 v[64:65], 0
	v_mov_b64_e32 v[66:67], 0
	v_mov_b64_e32 v[68:69], 0
	v_mov_b64_e32 v[74:75], 0
	v_mov_b64_e32 v[76:77], 0
	v_mov_b64_e32 v[82:83], 0
	v_mov_b64_e32 v[84:85], 0
	v_mov_b64_e32 v[90:91], 0
	v_mov_b64_e32 v[92:93], 0
	v_mov_b64_e32 v[98:99], 0
	v_mov_b64_e32 v[100:101], 0
	v_mov_b64_e32 v[106:107], 0
	v_mov_b64_e32 v[108:109], 0
	v_mov_b64_e32 v[114:115], 0
	v_mov_b64_e32 v[116:117], 0
	v_mov_b64_e32 v[122:123], 0
	v_mov_b64_e32 v[124:125], 0
	v_mov_b64_e32 v[70:71], 0
	v_mov_b64_e32 v[72:73], 0
	v_mov_b64_e32 v[78:79], 0
	v_mov_b64_e32 v[80:81], 0
	v_mov_b64_e32 v[86:87], 0
	v_mov_b64_e32 v[88:89], 0
	v_mov_b64_e32 v[94:95], 0
	v_mov_b64_e32 v[96:97], 0
	v_mov_b64_e32 v[102:103], 0
	v_mov_b64_e32 v[104:105], 0
	v_mov_b64_e32 v[110:111], 0
	v_mov_b64_e32 v[112:113], 0
	v_mov_b64_e32 v[118:119], 0
	v_mov_b64_e32 v[120:121], 0
	v_mov_b64_e32 v[126:127], 0
	v_mov_b64_e32 v[128:129], 0
	v_readfirstlane_b32 s98, v228
	s_lshr_b32 s98, s98, 8
	s_cmp_eq_u32 s98, 0
	s_cbranch_scc0 .Lprio_skip_1
	s_setprio 1

.LBB0_147:
	s_add_u32 s18, s16, 0xfffc0080
	s_addc_u32 s19, s17, -1
	s_cmp_eq_u32 s82, s99
	s_cselect_b32 s100, 0x800, 0
	s_sub_u32 s18, s18, s100
	s_subb_u32 s19, s19, 0
	s_sub_u32 s61, s61, s100
	s_subb_u32 s79, s79, 0
	s_add_i32 s83, 0, 0x10000
	v_add_u32_e32 v140, s83, v143
	ds_read_b128 v[146:149], v140
	ds_read_b128 v[150:153], v140 offset:1024
	ds_read_b128 v[154:157], v140 offset:2048
	ds_read_b128 v[158:161], v140 offset:3072
	s_cmp_eq_u32 s82, 12
	s_cselect_b32 s23, s12, s19
	s_cselect_b32 s22, s29, s18
	s_cselect_b32 s19, s9, s79
	s_cselect_b32 s18, s34, s61
	v_lshl_add_u64 v[140:141], s[16:17], 0, v[138:139]
	s_add_i32 m0, s15, 0xc000
	ds_read_b128 v[162:165], v145
	ds_read_b128 v[166:169], v145 offset:1024
	ds_read_b128 v[170:173], v145 offset:2048
	ds_read_b128 v[174:177], v145 offset:3072
	ds_read_b128 v[178:181], v145 offset:4096
	ds_read_b128 v[182:185], v145 offset:5120
	ds_read_b128 v[186:189], v145 offset:6144
	ds_read_b128 v[190:193], v145 offset:7168
	global_load_lds_dwordx4 v[140:141], off
	v_lshl_add_u64 v[140:141], s[16:17], 0, v[136:137]
	s_add_i32 m0, s15, 0xe000
	s_nop 0
	global_load_lds_dwordx4 v[140:141], off
	s_waitcnt lgkmcnt(8)
	s_waitcnt vmcnt(10)
	s_barrier
	s_waitcnt lgkmcnt(0)
	s_waitcnt lgkmcnt(0)
	v_mfma_f32_16x16x32_bf16 v[126:129], v[146:149], v[162:165], v[126:129]
	v_mfma_f32_16x16x32_bf16 v[118:121], v[154:157], v[162:165], v[118:121]
	v_mfma_f32_16x16x32_bf16 v[110:113], v[146:149], v[170:173], v[110:113]
	v_mfma_f32_16x16x32_bf16 v[102:105], v[154:157], v[170:173], v[102:105]
	v_mfma_f32_16x16x32_bf16 v[94:97], v[146:149], v[178:181], v[94:97]
	v_mfma_f32_16x16x32_bf16 v[86:89], v[154:157], v[178:181], v[86:89]
	v_mfma_f32_16x16x32_bf16 v[78:81], v[146:149], v[186:189], v[78:81]
	v_mfma_f32_16x16x32_bf16 v[70:73], v[154:157], v[186:189], v[70:73]
	v_mfma_f32_16x16x32_bf16 v[126:129], v[150:153], v[166:169], v[126:129]
	v_mfma_f32_16x16x32_bf16 v[118:121], v[158:161], v[166:169], v[118:121]
	v_mfma_f32_16x16x32_bf16 v[110:113], v[150:153], v[174:177], v[110:113]
	v_mfma_f32_16x16x32_bf16 v[102:105], v[158:161], v[174:177], v[102:105]
	v_mfma_f32_16x16x32_bf16 v[94:97], v[150:153], v[182:185], v[94:97]
	v_mfma_f32_16x16x32_bf16 v[86:89], v[158:161], v[182:185], v[86:89]
	v_mfma_f32_16x16x32_bf16 v[78:81], v[150:153], v[190:193], v[78:81]
	v_mfma_f32_16x16x32_bf16 v[70:73], v[158:161], v[190:193], v[70:73]
	s_barrier
	s_add_i32 s86, 0, 0x14000
	v_add_u32_e32 v140, s86, v143
	s_add_i32 s83, s83, s51
	ds_read_b128 v[194:197], v140
	ds_read_b128 v[208:211], v140 offset:1024
	ds_read_b128 v[212:215], v140 offset:2048
	ds_read_b128 v[216:219], v140 offset:3072
	v_lshl_add_u64 v[140:141], s[18:19], 0, v[16:17]
	s_mov_b32 m0, s83
	v_lshl_add_u64 v[220:221], s[18:19], 0, v[130:131]
	global_load_lds_dwordx4 v[140:141], off
	s_add_i32 m0, s83, 0x2000
	s_nop 0
	global_load_lds_dwordx4 v[220:221], off
	s_waitcnt vmcnt(10)
	s_barrier
	s_waitcnt lgkmcnt(0)
	s_waitcnt lgkmcnt(0)
	v_mfma_f32_16x16x32_bf16 v[122:125], v[194:197], v[162:165], v[122:125]
	v_mfma_f32_16x16x32_bf16 v[114:117], v[212:215], v[162:165], v[114:117]
	v_mfma_f32_16x16x32_bf16 v[106:109], v[194:197], v[170:173], v[106:109]
	v_mfma_f32_16x16x32_bf16 v[98:101], v[212:215], v[170:173], v[98:101]
	v_mfma_f32_16x16x32_bf16 v[90:93], v[194:197], v[178:181], v[90:93]
	v_mfma_f32_16x16x32_bf16 v[82:85], v[212:215], v[178:181], v[82:85]
	v_mfma_f32_16x16x32_bf16 v[74:77], v[194:197], v[186:189], v[74:77]
	v_mfma_f32_16x16x32_bf16 v[66:69], v[212:215], v[186:189], v[66:69]
	v_mfma_f32_16x16x32_bf16 v[122:125], v[208:211], v[166:169], v[122:125]
	v_mfma_f32_16x16x32_bf16 v[114:117], v[216:219], v[166:169], v[114:117]
	v_mfma_f32_16x16x32_bf16 v[106:109], v[208:211], v[174:177], v[106:109]
	v_mfma_f32_16x16x32_bf16 v[98:101], v[216:219], v[174:177], v[98:101]
	v_mfma_f32_16x16x32_bf16 v[90:93], v[208:211], v[182:185], v[90:93]
	v_mfma_f32_16x16x32_bf16 v[82:85], v[216:219], v[182:185], v[82:85]
	v_mfma_f32_16x16x32_bf16 v[74:77], v[208:211], v[190:193], v[74:77]
	v_mfma_f32_16x16x32_bf16 v[66:69], v[216:219], v[190:193], v[66:69]
	s_mov_b32 m0, s15
	v_lshl_add_u64 v[222:223], s[22:23], 0, v[134:135]
	s_barrier
	ds_read_b128 v[162:165], v145 offset:16384
	ds_read_b128 v[166:169], v145 offset:17408
	ds_read_b128 v[170:173], v145 offset:18432
	ds_read_b128 v[174:177], v145 offset:19456
	ds_read_b128 v[178:181], v145 offset:20480
	ds_read_b128 v[182:185], v145 offset:21504
	ds_read_b128 v[186:189], v145 offset:22528
	ds_read_b128 v[190:193], v145 offset:23552
	global_load_lds_dwordx4 v[222:223], off
	v_lshl_add_u64 v[224:225], s[22:23], 0, v[132:133]
	s_mov_b32 m0, s54
	s_nop 0
	global_load_lds_dwordx4 v[224:225], off
	s_barrier
	s_waitcnt lgkmcnt(0)
	s_waitcnt lgkmcnt(0)
	v_mfma_f32_16x16x32_bf16 v[62:65], v[146:149], v[162:165], v[62:65]
	v_mfma_f32_16x16x32_bf16 v[54:57], v[154:157], v[162:165], v[54:57]
	v_mfma_f32_16x16x32_bf16 v[46:49], v[146:149], v[170:173], v[46:49]
	v_mfma_f32_16x16x32_bf16 v[38:41], v[154:157], v[170:173], v[38:41]
	v_mfma_f32_16x16x32_bf16 v[30:33], v[146:149], v[178:181], v[30:33]
	v_mfma_f32_16x16x32_bf16 v[22:25], v[154:157], v[178:181], v[22:25]
	v_mfma_f32_16x16x32_bf16 v[12:15], v[146:149], v[186:189], v[12:15]
	v_mfma_f32_16x16x32_bf16 v[4:7], v[154:157], v[186:189], v[4:7]
	v_mfma_f32_16x16x32_bf16 v[62:65], v[150:153], v[166:169], v[62:65]
	v_mfma_f32_16x16x32_bf16 v[54:57], v[158:161], v[166:169], v[54:57]
	v_mfma_f32_16x16x32_bf16 v[46:49], v[150:153], v[174:177], v[46:49]
	v_mfma_f32_16x16x32_bf16 v[38:41], v[158:161], v[174:177], v[38:41]
	v_mfma_f32_16x16x32_bf16 v[30:33], v[150:153], v[182:185], v[30:33]
	v_mfma_f32_16x16x32_bf16 v[22:25], v[158:161], v[182:185], v[22:25]
	v_mfma_f32_16x16x32_bf16 v[12:15], v[150:153], v[190:193], v[12:15]
	v_mfma_f32_16x16x32_bf16 v[4:7], v[158:161], v[190:193], v[4:7]
	s_barrier
	s_add_u32 s84, s18, 0x40000
	s_addc_u32 s85, s19, 0
	s_add_i32 s83, s86, s51
	v_lshl_add_u64 v[146:147], s[84:85], 0, v[16:17]
	s_mov_b32 m0, s83
	s_nop 0
	global_load_lds_dwordx4 v[146:147], off
	v_lshl_add_u64 v[146:147], s[84:85], 0, v[130:131]
	s_add_i32 m0, s83, 0x2000
	s_nop 0
	global_load_lds_dwordx4 v[146:147], off
	s_waitcnt vmcnt(10)
	s_barrier
	v_mfma_f32_16x16x32_bf16 v[58:61], v[194:197], v[162:165], v[58:61]
	v_mfma_f32_16x16x32_bf16 v[50:53], v[212:215], v[162:165], v[50:53]
	v_mfma_f32_16x16x32_bf16 v[42:45], v[194:197], v[170:173], v[42:45]
	v_mfma_f32_16x16x32_bf16 v[34:37], v[212:215], v[170:173], v[34:37]
	v_mfma_f32_16x16x32_bf16 v[26:29], v[194:197], v[178:181], v[26:29]
	v_mfma_f32_16x16x32_bf16 v[18:21], v[212:215], v[178:181], v[18:21]
	v_mfma_f32_16x16x32_bf16 v[8:11], v[194:197], v[186:189], v[8:11]
	v_mfma_f32_16x16x32_bf16 v[0:3], v[212:215], v[186:189], v[0:3]
	v_mfma_f32_16x16x32_bf16 v[58:61], v[208:211], v[166:169], v[58:61]
	v_mfma_f32_16x16x32_bf16 v[50:53], v[216:219], v[166:169], v[50:53]
	v_mfma_f32_16x16x32_bf16 v[42:45], v[208:211], v[174:177], v[42:45]
	v_mfma_f32_16x16x32_bf16 v[34:37], v[216:219], v[174:177], v[34:37]
	v_mfma_f32_16x16x32_bf16 v[26:29], v[208:211], v[182:185], v[26:29]
	v_mfma_f32_16x16x32_bf16 v[18:21], v[216:219], v[182:185], v[18:21]
	v_mfma_f32_16x16x32_bf16 v[8:11], v[208:211], v[190:193], v[8:11]
	v_mfma_f32_16x16x32_bf16 v[0:3], v[216:219], v[190:193], v[0:3]
	s_add_i32 s83, 0, 0x18000
	v_add_u32_e32 v158, s83, v143
	s_barrier
	ds_read_b128 v[146:149], v158
	ds_read_b128 v[150:153], v158 offset:1024
	ds_read_b128 v[154:157], v158 offset:2048
	ds_read_b128 v[158:161], v158 offset:3072
	s_add_u32 s22, s22, 0x40000
	s_addc_u32 s23, s23, 0
	s_mov_b32 m0, s55
	v_lshl_add_u64 v[194:195], s[22:23], 0, v[134:135]
	ds_read_b128 v[162:165], v145 offset:32768
	ds_read_b128 v[166:169], v145 offset:33792
	ds_read_b128 v[170:173], v145 offset:34816
	ds_read_b128 v[174:177], v145 offset:35840
	ds_read_b128 v[178:181], v145 offset:36864
	ds_read_b128 v[182:185], v145 offset:37888
	ds_read_b128 v[186:189], v145 offset:38912
	ds_read_b128 v[190:193], v145 offset:39936
	global_load_lds_dwordx4 v[194:195], off
	v_lshl_add_u64 v[194:195], s[22:23], 0, v[132:133]
	s_mov_b32 m0, s56
	s_nop 0
	global_load_lds_dwordx4 v[194:195], off
	s_waitcnt lgkmcnt(8)
	s_waitcnt vmcnt(10)
	s_barrier
	s_waitcnt lgkmcnt(0)
	s_waitcnt lgkmcnt(0)
	v_mfma_f32_16x16x32_bf16 v[126:129], v[146:149], v[162:165], v[126:129]
	v_mfma_f32_16x16x32_bf16 v[118:121], v[154:157], v[162:165], v[118:121]
	v_mfma_f32_16x16x32_bf16 v[110:113], v[146:149], v[170:173], v[110:113]
	v_mfma_f32_16x16x32_bf16 v[102:105], v[154:157], v[170:173], v[102:105]
	v_mfma_f32_16x16x32_bf16 v[94:97], v[146:149], v[178:181], v[94:97]
	v_mfma_f32_16x16x32_bf16 v[86:89], v[154:157], v[178:181], v[86:89]
	v_mfma_f32_16x16x32_bf16 v[78:81], v[146:149], v[186:189], v[78:81]
	v_mfma_f32_16x16x32_bf16 v[70:73], v[154:157], v[186:189], v[70:73]
	v_mfma_f32_16x16x32_bf16 v[126:129], v[150:153], v[166:169], v[126:129]
	v_mfma_f32_16x16x32_bf16 v[118:121], v[158:161], v[166:169], v[118:121]
	v_mfma_f32_16x16x32_bf16 v[110:113], v[150:153], v[174:177], v[110:113]
	v_mfma_f32_16x16x32_bf16 v[102:105], v[158:161], v[174:177], v[102:105]
	v_mfma_f32_16x16x32_bf16 v[94:97], v[150:153], v[182:185], v[94:97]
	v_mfma_f32_16x16x32_bf16 v[86:89], v[158:161], v[182:185], v[86:89]
	v_mfma_f32_16x16x32_bf16 v[78:81], v[150:153], v[190:193], v[78:81]
	v_mfma_f32_16x16x32_bf16 v[70:73], v[158:161], v[190:193], v[70:73]
	s_barrier
	s_add_i32 s22, 0, 0x1c000
	s_add_i32 s23, s83, s51
	v_add_u32_e32 v216, s22, v143
	v_lshl_add_u64 v[140:141], v[140:141], 0, s[10:11]
	s_mov_b32 m0, s23
	ds_read_b128 v[194:197], v216
	ds_read_b128 v[208:211], v216 offset:1024
	ds_read_b128 v[212:215], v216 offset:2048
	ds_read_b128 v[216:219], v216 offset:3072
	global_load_lds_dwordx4 v[140:141], off
	v_lshl_add_u64 v[140:141], v[220:221], 0, s[10:11]
	s_add_i32 m0, s23, 0x2000
	s_nop 0
	global_load_lds_dwordx4 v[140:141], off
	s_waitcnt vmcnt(10)
	s_barrier
	s_waitcnt lgkmcnt(0)
	s_waitcnt lgkmcnt(0)
	v_mfma_f32_16x16x32_bf16 v[122:125], v[194:197], v[162:165], v[122:125]
	v_mfma_f32_16x16x32_bf16 v[114:117], v[212:215], v[162:165], v[114:117]
	v_mfma_f32_16x16x32_bf16 v[106:109], v[194:197], v[170:173], v[106:109]
	v_mfma_f32_16x16x32_bf16 v[98:101], v[212:215], v[170:173], v[98:101]
	v_mfma_f32_16x16x32_bf16 v[90:93], v[194:197], v[178:181], v[90:93]
	v_mfma_f32_16x16x32_bf16 v[82:85], v[212:215], v[178:181], v[82:85]
	v_mfma_f32_16x16x32_bf16 v[74:77], v[194:197], v[186:189], v[74:77]
	v_mfma_f32_16x16x32_bf16 v[66:69], v[212:215], v[186:189], v[66:69]
	v_mfma_f32_16x16x32_bf16 v[122:125], v[208:211], v[166:169], v[122:125]
	v_mfma_f32_16x16x32_bf16 v[114:117], v[216:219], v[166:169], v[114:117]
	v_mfma_f32_16x16x32_bf16 v[106:109], v[208:211], v[174:177], v[106:109]
	v_mfma_f32_16x16x32_bf16 v[98:101], v[216:219], v[174:177], v[98:101]
	v_mfma_f32_16x16x32_bf16 v[90:93], v[208:211], v[182:185], v[90:93]
	v_mfma_f32_16x16x32_bf16 v[82:85], v[216:219], v[182:185], v[82:85]
	v_mfma_f32_16x16x32_bf16 v[74:77], v[208:211], v[190:193], v[74:77]
	v_mfma_f32_16x16x32_bf16 v[66:69], v[216:219], v[190:193], v[66:69]
	s_mov_b32 m0, s57
	v_lshl_add_u64 v[140:141], v[222:223], 0, s[10:11]
	s_barrier
	ds_read_b128 v[162:165], v145 offset:49152
	ds_read_b128 v[166:169], v145 offset:50176
	ds_read_b128 v[170:173], v145 offset:51200
	ds_read_b128 v[174:177], v145 offset:52224
	ds_read_b128 v[178:181], v145 offset:53248
	ds_read_b128 v[182:185], v145 offset:54272
	ds_read_b128 v[186:189], v145 offset:55296
	ds_read_b128 v[190:193], v145 offset:56320
	global_load_lds_dwordx4 v[140:141], off
	v_lshl_add_u64 v[140:141], v[224:225], 0, s[10:11]
	s_mov_b32 m0, s58
	s_nop 0
	global_load_lds_dwordx4 v[140:141], off
	s_barrier
	s_waitcnt lgkmcnt(0)
	s_waitcnt lgkmcnt(0)
	v_mfma_f32_16x16x32_bf16 v[62:65], v[146:149], v[162:165], v[62:65]
	v_mfma_f32_16x16x32_bf16 v[54:57], v[154:157], v[162:165], v[54:57]
	v_mfma_f32_16x16x32_bf16 v[46:49], v[146:149], v[170:173], v[46:49]
	v_mfma_f32_16x16x32_bf16 v[38:41], v[154:157], v[170:173], v[38:41]
	v_mfma_f32_16x16x32_bf16 v[30:33], v[146:149], v[178:181], v[30:33]
	v_mfma_f32_16x16x32_bf16 v[22:25], v[154:157], v[178:181], v[22:25]
	v_mfma_f32_16x16x32_bf16 v[12:15], v[146:149], v[186:189], v[12:15]
	v_mfma_f32_16x16x32_bf16 v[4:7], v[154:157], v[186:189], v[4:7]
	v_mfma_f32_16x16x32_bf16 v[62:65], v[150:153], v[166:169], v[62:65]
	v_mfma_f32_16x16x32_bf16 v[54:57], v[158:161], v[166:169], v[54:57]
	v_mfma_f32_16x16x32_bf16 v[46:49], v[150:153], v[174:177], v[46:49]
	v_mfma_f32_16x16x32_bf16 v[38:41], v[158:161], v[174:177], v[38:41]
	v_mfma_f32_16x16x32_bf16 v[30:33], v[150:153], v[182:185], v[30:33]
	v_mfma_f32_16x16x32_bf16 v[22:25], v[158:161], v[182:185], v[22:25]
	v_mfma_f32_16x16x32_bf16 v[12:15], v[150:153], v[190:193], v[12:15]
	v_mfma_f32_16x16x32_bf16 v[4:7], v[158:161], v[190:193], v[4:7]
	s_barrier
	s_add_u32 s18, s18, 0x40080
	s_addc_u32 s19, s19, 0
	s_add_i32 s22, s22, s51
	v_lshl_add_u64 v[140:141], s[18:19], 0, v[16:17]
	s_mov_b32 m0, s22
	s_nop 0
	global_load_lds_dwordx4 v[140:141], off
	v_lshl_add_u64 v[140:141], s[18:19], 0, v[130:131]
	s_add_i32 m0, s22, 0x2000
	s_nop 0
	global_load_lds_dwordx4 v[140:141], off
	s_waitcnt vmcnt(10)
	s_barrier
	v_mfma_f32_16x16x32_bf16 v[58:61], v[194:197], v[162:165], v[58:61]
	v_mfma_f32_16x16x32_bf16 v[50:53], v[212:215], v[162:165], v[50:53]
	v_mfma_f32_16x16x32_bf16 v[42:45], v[194:197], v[170:173], v[42:45]
	v_mfma_f32_16x16x32_bf16 v[34:37], v[212:215], v[170:173], v[34:37]
	v_mfma_f32_16x16x32_bf16 v[26:29], v[194:197], v[178:181], v[26:29]
	v_mfma_f32_16x16x32_bf16 v[18:21], v[212:215], v[178:181], v[18:21]
	v_mfma_f32_16x16x32_bf16 v[8:11], v[194:197], v[186:189], v[8:11]
	v_mfma_f32_16x16x32_bf16 v[0:3], v[212:215], v[186:189], v[0:3]
	v_mfma_f32_16x16x32_bf16 v[58:61], v[208:211], v[166:169], v[58:61]
	v_mfma_f32_16x16x32_bf16 v[50:53], v[216:219], v[166:169], v[50:53]
	v_mfma_f32_16x16x32_bf16 v[42:45], v[208:211], v[174:177], v[42:45]
	v_mfma_f32_16x16x32_bf16 v[34:37], v[216:219], v[174:177], v[34:37]
	v_mfma_f32_16x16x32_bf16 v[26:29], v[208:211], v[182:185], v[26:29]
	v_mfma_f32_16x16x32_bf16 v[18:21], v[216:219], v[182:185], v[18:21]
	v_mfma_f32_16x16x32_bf16 v[8:11], v[208:211], v[190:193], v[8:11]
	v_mfma_f32_16x16x32_bf16 v[0:3], v[216:219], v[190:193], v[0:3]
	s_add_i32 s82, s82, 2
	s_add_u32 s61, s61, 0x100
	s_addc_u32 s79, s79, 0
	s_add_u32 s16, s16, 0x100
	s_addc_u32 s17, s17, 0
	s_sub_u32 s16, s16, s100
	s_subb_u32 s17, s17, 0
	s_cmp_gt_u32 s82, 13
	s_barrier
	s_cbranch_scc0 .LBB0_147
	v_mul_f32_e32 v208, 0xbfb8aa3b, v126
	v_mul_f32_e32 v209, 0xbfb8aa3b, v127
	v_mul_f32_e32 v210, 0xbfb8aa3b, v128
	v_mul_f32_e32 v211, 0xbfb8aa3b, v129
	v_mul_f32_e32 v212, 0xbfb8aa3b, v118
	v_mul_f32_e32 v213, 0xbfb8aa3b, v119
	v_mul_f32_e32 v214, 0xbfb8aa3b, v120
	v_mul_f32_e32 v215, 0xbfb8aa3b, v121
	v_exp_f32_e32 v208, v208
	v_exp_f32_e32 v209, v209
	v_exp_f32_e32 v210, v210
	v_exp_f32_e32 v211, v211
	v_exp_f32_e32 v212, v212
	v_exp_f32_e32 v213, v213
	v_exp_f32_e32 v214, v214
	v_exp_f32_e32 v215, v215
	v_add_f32_e32 v208, 1.0, v208
	v_add_f32_e32 v209, 1.0, v209
	v_add_f32_e32 v210, 1.0, v210
	v_add_f32_e32 v211, 1.0, v211
	v_add_f32_e32 v212, 1.0, v212
	v_add_f32_e32 v213, 1.0, v213
	v_add_f32_e32 v214, 1.0, v214
	v_add_f32_e32 v215, 1.0, v215
	v_rcp_f32_e32 v208, v208
	v_rcp_f32_e32 v209, v209
	v_rcp_f32_e32 v210, v210
	v_rcp_f32_e32 v211, v211
	v_rcp_f32_e32 v212, v212
	v_rcp_f32_e32 v213, v213
	v_rcp_f32_e32 v214, v214
	v_rcp_f32_e32 v215, v215
	v_mul_f32_e32 v216, v126, v208
	v_mul_f32_e32 v217, v127, v209
	v_mul_f32_e32 v218, v128, v210
	v_mul_f32_e32 v219, v129, v211
	v_mul_f32_e32 v220, v118, v212
	v_mul_f32_e32 v221, v119, v213
	v_mul_f32_e32 v222, v120, v214
	v_mul_f32_e32 v223, v121, v215
	v_mul_f32_e32 v216, v216, v122
	v_mul_f32_e32 v217, v217, v123
	v_mul_f32_e32 v218, v218, v124
	v_mul_f32_e32 v219, v219, v125
	v_mul_f32_e32 v220, v220, v114
	v_mul_f32_e32 v221, v221, v115
	v_mul_f32_e32 v222, v222, v116
	v_mul_f32_e32 v223, v223, v117
	v_lshl_or_b32 v148, s2, 7, v144
	v_lshl_add_u32 v146, s14, 8, v142
	v_ashrrev_i32_e32 v149, 31, v148
	v_mov_b64_e32 v[140:141], s[94:95]
	v_mad_i64_i32 v[150:151], s[16:17], v146, s65, v[140:141]
	v_lshlrev_b64 v[114:115], 1, v[148:149]
	v_lshl_add_u64 v[120:121], v[150:151], 0, v[114:115]
	v_cvt_pk_bf16_f32 v116, v216, v217
	v_cvt_pk_bf16_f32 v117, v218, v219
	v_cvt_pk_bf16_f32 v118, v220, v221
	v_cvt_pk_bf16_f32 v119, v222, v223
	global_store_dwordx4 v[120:121], v[116:119], off
	v_mul_f32_e32 v208, 0xbfb8aa3b, v110
	v_mul_f32_e32 v209, 0xbfb8aa3b, v111
	v_mul_f32_e32 v210, 0xbfb8aa3b, v112
	v_mul_f32_e32 v211, 0xbfb8aa3b, v113
	v_mul_f32_e32 v212, 0xbfb8aa3b, v102
	v_mul_f32_e32 v213, 0xbfb8aa3b, v103
	v_mul_f32_e32 v214, 0xbfb8aa3b, v104
	v_mul_f32_e32 v215, 0xbfb8aa3b, v105
	v_exp_f32_e32 v208, v208
	v_exp_f32_e32 v209, v209
	v_exp_f32_e32 v210, v210
	v_exp_f32_e32 v211, v211
	v_exp_f32_e32 v212, v212
	v_exp_f32_e32 v213, v213
	v_exp_f32_e32 v214, v214
	v_exp_f32_e32 v215, v215
	v_add_f32_e32 v208, 1.0, v208
	v_add_f32_e32 v209, 1.0, v209
	v_add_f32_e32 v210, 1.0, v210
	v_add_f32_e32 v211, 1.0, v211
	v_add_f32_e32 v212, 1.0, v212
	v_add_f32_e32 v213, 1.0, v213
	v_add_f32_e32 v214, 1.0, v214
	v_add_f32_e32 v215, 1.0, v215
	v_rcp_f32_e32 v208, v208
	v_rcp_f32_e32 v209, v209
	v_rcp_f32_e32 v210, v210
	v_rcp_f32_e32 v211, v211
	v_rcp_f32_e32 v212, v212
	v_rcp_f32_e32 v213, v213
	v_rcp_f32_e32 v214, v214
	v_rcp_f32_e32 v215, v215
	v_mul_f32_e32 v216, v110, v208
	v_mul_f32_e32 v217, v111, v209
	v_mul_f32_e32 v218, v112, v210
	v_mul_f32_e32 v219, v113, v211
	v_mul_f32_e32 v220, v102, v212
	v_mul_f32_e32 v221, v103, v213
	v_mul_f32_e32 v222, v104, v214
	v_mul_f32_e32 v223, v105, v215
	v_mul_f32_e32 v216, v216, v106
	v_mul_f32_e32 v217, v217, v107
	v_mul_f32_e32 v218, v218, v108
	v_mul_f32_e32 v219, v219, v109
	v_mul_f32_e32 v220, v220, v98
	v_mul_f32_e32 v221, v221, v99
	v_mul_f32_e32 v222, v222, v100
	v_mul_f32_e32 v223, v223, v101
	v_or_b32_e32 v116, 16, v146
	v_mad_i64_i32 v[116:117], s[16:17], v116, s65, v[140:141]
	v_lshl_add_u64 v[102:103], v[116:117], 0, v[114:115]
	v_cvt_pk_bf16_f32 v98, v216, v217
	v_cvt_pk_bf16_f32 v99, v218, v219
	v_cvt_pk_bf16_f32 v100, v220, v221
	v_cvt_pk_bf16_f32 v101, v222, v223
	global_store_dwordx4 v[102:103], v[98:101], off
	v_mul_f32_e32 v208, 0xbfb8aa3b, v94
	v_mul_f32_e32 v209, 0xbfb8aa3b, v95
	v_mul_f32_e32 v210, 0xbfb8aa3b, v96
	v_mul_f32_e32 v211, 0xbfb8aa3b, v97
	v_mul_f32_e32 v212, 0xbfb8aa3b, v86
	v_mul_f32_e32 v213, 0xbfb8aa3b, v87
	v_mul_f32_e32 v214, 0xbfb8aa3b, v88
	v_mul_f32_e32 v215, 0xbfb8aa3b, v89
	v_exp_f32_e32 v208, v208
	v_exp_f32_e32 v209, v209
	v_exp_f32_e32 v210, v210
	v_exp_f32_e32 v211, v211
	v_exp_f32_e32 v212, v212
	v_exp_f32_e32 v213, v213
	v_exp_f32_e32 v214, v214
	v_exp_f32_e32 v215, v215
	v_add_f32_e32 v208, 1.0, v208
	v_add_f32_e32 v209, 1.0, v209
	v_add_f32_e32 v210, 1.0, v210
	v_add_f32_e32 v211, 1.0, v211
	v_add_f32_e32 v212, 1.0, v212
	v_add_f32_e32 v213, 1.0, v213
	v_add_f32_e32 v214, 1.0, v214
	v_add_f32_e32 v215, 1.0, v215
	v_rcp_f32_e32 v208, v208
	v_rcp_f32_e32 v209, v209
	v_rcp_f32_e32 v210, v210
	v_rcp_f32_e32 v211, v211
	v_rcp_f32_e32 v212, v212
	v_rcp_f32_e32 v213, v213
	v_rcp_f32_e32 v214, v214
	v_rcp_f32_e32 v215, v215
	v_mul_f32_e32 v216, v94, v208
	v_mul_f32_e32 v217, v95, v209
	v_mul_f32_e32 v218, v96, v210
	v_mul_f32_e32 v219, v97, v211
	v_mul_f32_e32 v220, v86, v212
	v_mul_f32_e32 v221, v87, v213
	v_mul_f32_e32 v222, v88, v214
	v_mul_f32_e32 v223, v89, v215
	v_mul_f32_e32 v216, v216, v90
	v_mul_f32_e32 v217, v217, v91
	v_mul_f32_e32 v218, v218, v92
	v_mul_f32_e32 v219, v219, v93
	v_mul_f32_e32 v220, v220, v82
	v_mul_f32_e32 v221, v221, v83
	v_mul_f32_e32 v222, v222, v84
	v_mul_f32_e32 v223, v223, v85
	v_or_b32_e32 v98, 32, v146
	v_mad_i64_i32 v[98:99], s[16:17], v98, s65, v[140:141]
	v_lshl_add_u64 v[86:87], v[98:99], 0, v[114:115]
	v_cvt_pk_bf16_f32 v82, v216, v217
	v_cvt_pk_bf16_f32 v83, v218, v219
	v_cvt_pk_bf16_f32 v84, v220, v221
	v_cvt_pk_bf16_f32 v85, v222, v223
	global_store_dwordx4 v[86:87], v[82:85], off
	v_mul_f32_e32 v208, 0xbfb8aa3b, v78
	v_mul_f32_e32 v209, 0xbfb8aa3b, v79
	v_mul_f32_e32 v210, 0xbfb8aa3b, v80
	v_mul_f32_e32 v211, 0xbfb8aa3b, v81
	v_mul_f32_e32 v212, 0xbfb8aa3b, v70
	v_mul_f32_e32 v213, 0xbfb8aa3b, v71
	v_mul_f32_e32 v214, 0xbfb8aa3b, v72
	v_mul_f32_e32 v215, 0xbfb8aa3b, v73
	v_exp_f32_e32 v208, v208
	v_exp_f32_e32 v209, v209
	v_exp_f32_e32 v210, v210
	v_exp_f32_e32 v211, v211
	v_exp_f32_e32 v212, v212
	v_exp_f32_e32 v213, v213
	v_exp_f32_e32 v214, v214
	v_exp_f32_e32 v215, v215
	v_add_f32_e32 v208, 1.0, v208
	v_add_f32_e32 v209, 1.0, v209
	v_add_f32_e32 v210, 1.0, v210
	v_add_f32_e32 v211, 1.0, v211
	v_add_f32_e32 v212, 1.0, v212
	v_add_f32_e32 v213, 1.0, v213
	v_add_f32_e32 v214, 1.0, v214
	v_add_f32_e32 v215, 1.0, v215
	v_rcp_f32_e32 v208, v208
	v_rcp_f32_e32 v209, v209
	v_rcp_f32_e32 v210, v210
	v_rcp_f32_e32 v211, v211
	v_rcp_f32_e32 v212, v212
	v_rcp_f32_e32 v213, v213
	v_rcp_f32_e32 v214, v214
	v_rcp_f32_e32 v215, v215
	v_mul_f32_e32 v216, v78, v208
	v_mul_f32_e32 v217, v79, v209
	v_mul_f32_e32 v218, v80, v210
	v_mul_f32_e32 v219, v81, v211
	v_mul_f32_e32 v220, v70, v212
	v_mul_f32_e32 v221, v71, v213
	v_mul_f32_e32 v222, v72, v214
	v_mul_f32_e32 v223, v73, v215
	v_mul_f32_e32 v216, v216, v74
	v_mul_f32_e32 v217, v217, v75
	v_mul_f32_e32 v218, v218, v76
	v_mul_f32_e32 v219, v219, v77
	v_mul_f32_e32 v220, v220, v66
	v_mul_f32_e32 v221, v221, v67
	v_mul_f32_e32 v222, v222, v68
	v_mul_f32_e32 v223, v223, v69
	v_or_b32_e32 v82, 48, v146
	v_mad_i64_i32 v[82:83], s[16:17], v82, s65, v[140:141]
	v_lshl_add_u64 v[70:71], v[82:83], 0, v[114:115]
	v_cvt_pk_bf16_f32 v66, v216, v217
	v_cvt_pk_bf16_f32 v67, v218, v219
	v_cvt_pk_bf16_f32 v68, v220, v221
	v_cvt_pk_bf16_f32 v69, v222, v223
	global_store_dwordx4 v[70:71], v[66:69], off
	v_mul_f32_e32 v208, 0xbfb8aa3b, v62
	v_mul_f32_e32 v209, 0xbfb8aa3b, v63
	v_mul_f32_e32 v210, 0xbfb8aa3b, v64
	v_mul_f32_e32 v211, 0xbfb8aa3b, v65
	v_mul_f32_e32 v212, 0xbfb8aa3b, v54
	v_mul_f32_e32 v213, 0xbfb8aa3b, v55
	v_mul_f32_e32 v214, 0xbfb8aa3b, v56
	v_mul_f32_e32 v215, 0xbfb8aa3b, v57
	v_exp_f32_e32 v208, v208
	v_exp_f32_e32 v209, v209
	v_exp_f32_e32 v210, v210
	v_exp_f32_e32 v211, v211
	v_exp_f32_e32 v212, v212
	v_exp_f32_e32 v213, v213
	v_exp_f32_e32 v214, v214
	v_exp_f32_e32 v215, v215
	v_add_f32_e32 v208, 1.0, v208
	v_add_f32_e32 v209, 1.0, v209
	v_add_f32_e32 v210, 1.0, v210
	v_add_f32_e32 v211, 1.0, v211
	v_add_f32_e32 v212, 1.0, v212
	v_add_f32_e32 v213, 1.0, v213
	v_add_f32_e32 v214, 1.0, v214
	v_add_f32_e32 v215, 1.0, v215
	v_rcp_f32_e32 v208, v208
	v_rcp_f32_e32 v209, v209
	v_rcp_f32_e32 v210, v210
	v_rcp_f32_e32 v211, v211
	v_rcp_f32_e32 v212, v212
	v_rcp_f32_e32 v213, v213
	v_rcp_f32_e32 v214, v214
	v_rcp_f32_e32 v215, v215
	v_mul_f32_e32 v216, v62, v208
	v_mul_f32_e32 v217, v63, v209
	v_mul_f32_e32 v218, v64, v210
	v_mul_f32_e32 v219, v65, v211
	v_mul_f32_e32 v220, v54, v212
	v_mul_f32_e32 v221, v55, v213
	v_mul_f32_e32 v222, v56, v214
	v_mul_f32_e32 v223, v57, v215
	v_mul_f32_e32 v216, v216, v58
	v_mul_f32_e32 v217, v217, v59
	v_mul_f32_e32 v218, v218, v60
	v_mul_f32_e32 v219, v219, v61
	v_mul_f32_e32 v220, v220, v50
	v_mul_f32_e32 v221, v221, v51
	v_mul_f32_e32 v222, v222, v52
	v_mul_f32_e32 v223, v223, v53
	v_add_u32_e32 v66, 0x80, v146
	v_mad_i64_i32 v[66:67], s[16:17], v66, s65, v[140:141]
	v_lshl_add_u64 v[54:55], v[66:67], 0, v[114:115]
	v_cvt_pk_bf16_f32 v50, v216, v217
	v_cvt_pk_bf16_f32 v51, v218, v219
	v_cvt_pk_bf16_f32 v52, v220, v221
	v_cvt_pk_bf16_f32 v53, v222, v223
	global_store_dwordx4 v[54:55], v[50:53], off
	v_mul_f32_e32 v208, 0xbfb8aa3b, v46
	v_mul_f32_e32 v209, 0xbfb8aa3b, v47
	v_mul_f32_e32 v210, 0xbfb8aa3b, v48
	v_mul_f32_e32 v211, 0xbfb8aa3b, v49
	v_mul_f32_e32 v212, 0xbfb8aa3b, v38
	v_mul_f32_e32 v213, 0xbfb8aa3b, v39
	v_mul_f32_e32 v214, 0xbfb8aa3b, v40
	v_mul_f32_e32 v215, 0xbfb8aa3b, v41
	v_exp_f32_e32 v208, v208
	v_exp_f32_e32 v209, v209
	v_exp_f32_e32 v210, v210
	v_exp_f32_e32 v211, v211
	v_exp_f32_e32 v212, v212
	v_exp_f32_e32 v213, v213
	v_exp_f32_e32 v214, v214
	v_exp_f32_e32 v215, v215
	v_add_f32_e32 v208, 1.0, v208
	v_add_f32_e32 v209, 1.0, v209
	v_add_f32_e32 v210, 1.0, v210
	v_add_f32_e32 v211, 1.0, v211
	v_add_f32_e32 v212, 1.0, v212
	v_add_f32_e32 v213, 1.0, v213
	v_add_f32_e32 v214, 1.0, v214
	v_add_f32_e32 v215, 1.0, v215
	v_rcp_f32_e32 v208, v208
	v_rcp_f32_e32 v209, v209
	v_rcp_f32_e32 v210, v210
	v_rcp_f32_e32 v211, v211
	v_rcp_f32_e32 v212, v212
	v_rcp_f32_e32 v213, v213
	v_rcp_f32_e32 v214, v214
	v_rcp_f32_e32 v215, v215
	v_mul_f32_e32 v216, v46, v208
	v_mul_f32_e32 v217, v47, v209
	v_mul_f32_e32 v218, v48, v210
	v_mul_f32_e32 v219, v49, v211
	v_mul_f32_e32 v220, v38, v212
	v_mul_f32_e32 v221, v39, v213
	v_mul_f32_e32 v222, v40, v214
	v_mul_f32_e32 v223, v41, v215
	v_mul_f32_e32 v216, v216, v42
	v_mul_f32_e32 v217, v217, v43
	v_mul_f32_e32 v218, v218, v44
	v_mul_f32_e32 v219, v219, v45
	v_mul_f32_e32 v220, v220, v34
	v_mul_f32_e32 v221, v221, v35
	v_mul_f32_e32 v222, v222, v36
	v_mul_f32_e32 v223, v223, v37
	v_add_u32_e32 v50, 0x90, v146
	v_mad_i64_i32 v[50:51], s[16:17], v50, s65, v[140:141]
	v_lshl_add_u64 v[38:39], v[50:51], 0, v[114:115]
	v_cvt_pk_bf16_f32 v34, v216, v217
	v_cvt_pk_bf16_f32 v35, v218, v219
	v_cvt_pk_bf16_f32 v36, v220, v221
	v_cvt_pk_bf16_f32 v37, v222, v223
	global_store_dwordx4 v[38:39], v[34:37], off
	v_mul_f32_e32 v208, 0xbfb8aa3b, v30
	v_mul_f32_e32 v209, 0xbfb8aa3b, v31
	v_mul_f32_e32 v210, 0xbfb8aa3b, v32
	v_mul_f32_e32 v211, 0xbfb8aa3b, v33
	v_mul_f32_e32 v212, 0xbfb8aa3b, v22
	v_mul_f32_e32 v213, 0xbfb8aa3b, v23
	v_mul_f32_e32 v214, 0xbfb8aa3b, v24
	v_mul_f32_e32 v215, 0xbfb8aa3b, v25
	v_exp_f32_e32 v208, v208
	v_exp_f32_e32 v209, v209
	v_exp_f32_e32 v210, v210
	v_exp_f32_e32 v211, v211
	v_exp_f32_e32 v212, v212
	v_exp_f32_e32 v213, v213
	v_exp_f32_e32 v214, v214
	v_exp_f32_e32 v215, v215
	v_add_f32_e32 v208, 1.0, v208
	v_add_f32_e32 v209, 1.0, v209
	v_add_f32_e32 v210, 1.0, v210
	v_add_f32_e32 v211, 1.0, v211
	v_add_f32_e32 v212, 1.0, v212
	v_add_f32_e32 v213, 1.0, v213
	v_add_f32_e32 v214, 1.0, v214
	v_add_f32_e32 v215, 1.0, v215
	v_rcp_f32_e32 v208, v208
	v_rcp_f32_e32 v209, v209
	v_rcp_f32_e32 v210, v210
	v_rcp_f32_e32 v211, v211
	v_rcp_f32_e32 v212, v212
	v_rcp_f32_e32 v213, v213
	v_rcp_f32_e32 v214, v214
	v_rcp_f32_e32 v215, v215
	v_mul_f32_e32 v216, v30, v208
	v_mul_f32_e32 v217, v31, v209
	v_mul_f32_e32 v218, v32, v210
	v_mul_f32_e32 v219, v33, v211
	v_mul_f32_e32 v220, v22, v212
	v_mul_f32_e32 v221, v23, v213
	v_mul_f32_e32 v222, v24, v214
	v_mul_f32_e32 v223, v25, v215
	v_mul_f32_e32 v216, v216, v26
	v_mul_f32_e32 v217, v217, v27
	v_mul_f32_e32 v218, v218, v28
	v_mul_f32_e32 v219, v219, v29
	v_mul_f32_e32 v220, v220, v18
	v_mul_f32_e32 v221, v221, v19
	v_mul_f32_e32 v222, v222, v20
	v_mul_f32_e32 v223, v223, v21
	v_add_u32_e32 v34, 0xa0, v146
	v_mad_i64_i32 v[34:35], s[16:17], v34, s65, v[140:141]
	v_lshl_add_u64 v[22:23], v[34:35], 0, v[114:115]
	v_cvt_pk_bf16_f32 v18, v216, v217
	v_cvt_pk_bf16_f32 v19, v218, v219
	v_cvt_pk_bf16_f32 v20, v220, v221
	v_cvt_pk_bf16_f32 v21, v222, v223
	global_store_dwordx4 v[22:23], v[18:21], off
	v_mul_f32_e32 v208, 0xbfb8aa3b, v12
	v_mul_f32_e32 v209, 0xbfb8aa3b, v13
	v_mul_f32_e32 v210, 0xbfb8aa3b, v14
	v_mul_f32_e32 v211, 0xbfb8aa3b, v15
	v_mul_f32_e32 v212, 0xbfb8aa3b, v4
	v_mul_f32_e32 v213, 0xbfb8aa3b, v5
	v_mul_f32_e32 v214, 0xbfb8aa3b, v6
	v_mul_f32_e32 v215, 0xbfb8aa3b, v7
	v_exp_f32_e32 v208, v208
	v_exp_f32_e32 v209, v209
	v_exp_f32_e32 v210, v210
	v_exp_f32_e32 v211, v211
	v_exp_f32_e32 v212, v212
	v_exp_f32_e32 v213, v213
	v_exp_f32_e32 v214, v214
	v_exp_f32_e32 v215, v215
	v_add_f32_e32 v208, 1.0, v208
	v_add_f32_e32 v209, 1.0, v209
	v_add_f32_e32 v210, 1.0, v210
	v_add_f32_e32 v211, 1.0, v211
	v_add_f32_e32 v212, 1.0, v212
	v_add_f32_e32 v213, 1.0, v213
	v_add_f32_e32 v214, 1.0, v214
	v_add_f32_e32 v215, 1.0, v215
	v_rcp_f32_e32 v208, v208
	v_rcp_f32_e32 v209, v209
	v_rcp_f32_e32 v210, v210
	v_rcp_f32_e32 v211, v211
	v_rcp_f32_e32 v212, v212
	v_rcp_f32_e32 v213, v213
	v_rcp_f32_e32 v214, v214
	v_rcp_f32_e32 v215, v215
	v_mul_f32_e32 v216, v12, v208
	v_mul_f32_e32 v217, v13, v209
	v_mul_f32_e32 v218, v14, v210
	v_mul_f32_e32 v219, v15, v211
	v_mul_f32_e32 v220, v4, v212
	v_mul_f32_e32 v221, v5, v213
	v_mul_f32_e32 v222, v6, v214
	v_mul_f32_e32 v223, v7, v215
	v_mul_f32_e32 v216, v216, v8
	v_mul_f32_e32 v217, v217, v9
	v_mul_f32_e32 v218, v218, v10
	v_mul_f32_e32 v219, v219, v11
	v_mul_f32_e32 v220, v220, v0
	v_mul_f32_e32 v221, v221, v1
	v_mul_f32_e32 v222, v222, v2
	v_mul_f32_e32 v223, v223, v3
	v_add_u32_e32 v18, 0xb0, v146
	v_mad_i64_i32 v[18:19], s[16:17], v18, s65, v[140:141]
	v_lshl_add_u64 v[4:5], v[18:19], 0, v[114:115]
	v_cvt_pk_bf16_f32 v0, v216, v217
	v_cvt_pk_bf16_f32 v1, v218, v219
	v_cvt_pk_bf16_f32 v2, v220, v221
	v_cvt_pk_bf16_f32 v3, v222, v223
	global_store_dwordx4 v[4:5], v[0:3], off
	s_and_b64 vcc, exec, s[38:39]
	s_mov_b32 s2, s8
	s_mov_b32 s14, s28
	s_mov_b64 s[16:17], s[42:43]
	s_mov_b64 s[18:19], s[40:41]
	s_cbranch_vccz .LBB0_144
	s_waitcnt vmcnt(0)
	s_cmpk_gt_u32 s48, 0xff
	s_cbranch_scc1 .LBB0_151
	s_barrier
